# v43 plus 64-byte alignment of the row-phase (P1,P3,P8,P11) and compress (P4) loop heads
# baseline (speedup 1.0000x reference)
; template <bool BF> __device__ __forceinline__ unsigned pk2(float lo, float hi) { return BF ? pk_bf2(lo, hi) : pk_h2(lo, hi); }
; template <bool BF, bool IN_F16> __device__ __forceinline__ void norm_mod_rows(const void* __restrict__ Xv, const float* __restrict__ gw, const float* __restrict__ mod, int sh_off, int sc_off,
;                                               h16* __restrict__ H, int G, int bid) {
;     const int lane = threadIdx.x & 63, wave = threadIdx.x >> 6;
;     for (int r = bid * 8 + wave; r < NT; r += G * 8) {
;         const int b = r >> 13; f32x4 v[8]; float ss = 0.f;
;         if (IN_F16) { const h16* xr = (const h16*)Xv + (size_t)r * DM;
; #pragma unroll
;             for (int i = 0; i < 8; ++i) { const half4 hv = *(const half4*)(xr + 4 * (lane + 64 * i)); v[i] = (f32x4){(float)hv[0], (float)hv[1], (float)hv[2], (float)hv[3]}; } }
;         else { const float* xr = (const float*)Xv + (size_t)r * DM;
; #pragma unroll
;             for (int i = 0; i < 8; ++i) v[i] = *(const f32x4*)(xr + 4 * (lane + 64 * i)); }
; #pragma unroll
;         for (int i = 0; i < 8; ++i) ss += v[i][0] * v[i][0] + v[i][1] * v[i][1] + v[i][2] * v[i][2] + v[i][3] * v[i][3];
;         ss = wave_sum(ss); const float rstd = rsqrtf(ss * (1.f / DM) + EPS);
;         const float* mb = mod + (size_t)b * 12288;
; #pragma unroll
;         for (int i = 0; i < 8; ++i) { const int c = 4 * (lane + 64 * i);
;             const f32x4 g = *(const f32x4*)(gw + c), sh = *(const f32x4*)(mb + sh_off + c), sc = *(const f32x4*)(mb + sc_off + c);
;             const f32x4 o = (v[i] * rstd) * g * (1.f + sc) + sh;
;             u32x2 w; w.x = pg8::pk2<BF>(o[0], o[1]); w.y = pg8::pk2<BF>(o[2], o[3]);
;             *(u32x2*)(H + (size_t)r * DM + c) = w; }
.LBB0_188:
.LBB0_189:
	s_add_u32 s68, s24, 0x4000
	s_addc_u32 s69, s25, 0
	s_cmp_lt_i32 s26, 2
	s_cselect_b64 s[0:1], -1, 0
	s_cmp_gt_i32 s27, 1
	s_cselect_b64 s[4:5], -1, 0
	s_and_b64 s[0:1], s[0:1], s[4:5]
	s_andn2_b64 vcc, exec, s[0:1]
	s_cbranch_vccnz .LBB0_257
	v_lshrrev_b32_e32 v2, 6, v1
	v_lshl_add_u32 v66, s2, 3, v2
	s_mov_b32 s0, 0x8000
	v_cmp_gt_i32_e32 vcc, s0, v66
	s_and_saveexec_b64 s[4:5], vcc
	s_cbranch_execz .LBB0_193
	s_load_dwordx2 s[0:1], s[96:97], 0x20
	v_lshlrev_b32_e32 v2, 2, v1
	v_and_b32_e32 v34, 0xfc, v2
	v_lshlrev_b32_e32 v18, 2, v34
	v_or_b32_e32 v36, 0x400, v34
	v_or_b32_e32 v38, 0x500, v34
	v_or_b32_e32 v40, 0x600, v34
	s_waitcnt lgkmcnt(0)
	global_load_dwordx4 v[2:5], v18, s[0:1]
	global_load_dwordx4 v[6:9], v18, s[0:1] offset:1024
	global_load_dwordx4 v[10:13], v18, s[0:1] offset:2048
	global_load_dwordx4 v[14:17], v18, s[0:1] offset:3072
	v_or_b32_e32 v42, 0x700, v34
	v_lshlrev_b32_e32 v26, 2, v36
	v_lshlrev_b32_e32 v27, 2, v38
	v_lshlrev_b32_e32 v35, 2, v40
	global_load_dwordx4 v[18:21], v26, s[0:1]
	global_load_dwordx4 v[22:25], v27, s[0:1]
	v_lshlrev_b32_e32 v37, 2, v42
	global_load_dwordx4 v[26:29], v35, s[0:1]
	global_load_dwordx4 v[30:33], v37, s[0:1]
	v_mbcnt_lo_u32_b32 v35, -1, 0
	v_mbcnt_hi_u32_b32 v35, -1, v35
	v_and_b32_e32 v37, 64, v35
	v_add_u32_e32 v37, 64, v37
	v_xor_b32_e32 v39, 1, v35
	v_cmp_lt_i32_e32 vcc, v39, v37
	v_ashrrev_i32_e32 v67, 31, v66
	s_load_dwordx2 s[0:1], s[96:97], 0x0
	v_cndmask_b32_e32 v39, v35, v39, vcc
	v_lshlrev_b32_e32 v88, 2, v39
	v_xor_b32_e32 v39, 2, v35
	v_cmp_lt_i32_e32 vcc, v39, v37
	v_lshlrev_b64 v[50:51], 12, v[66:67]
	s_mov_b64 s[8:9], 0x6564000
	v_cndmask_b32_e32 v39, v35, v39, vcc
	v_lshlrev_b32_e32 v89, 2, v39
	v_xor_b32_e32 v39, 4, v35
	v_cmp_lt_i32_e32 vcc, v39, v37
	s_lshl_b32 s6, s95, 3
	v_or_b32_e32 v44, 0x100, v34
	v_cndmask_b32_e32 v39, v35, v39, vcc
	v_lshlrev_b32_e32 v90, 2, v39
	v_xor_b32_e32 v39, 8, v35
	v_cmp_lt_i32_e32 vcc, v39, v37
	v_or_b32_e32 v46, 0x200, v34
	v_or_b32_e32 v48, 0x300, v34
	v_cndmask_b32_e32 v39, v35, v39, vcc
	v_lshlrev_b32_e32 v91, 2, v39
	v_xor_b32_e32 v39, 16, v35
	v_cmp_lt_i32_e32 vcc, v39, v37
	s_ashr_i32 s7, s6, 31
	v_mov_b32_e32 v69, 0
	v_cndmask_b32_e32 v39, v35, v39, vcc
	v_lshlrev_b32_e32 v92, 2, v39
	v_xor_b32_e32 v39, 32, v35
	v_cmp_lt_i32_e32 vcc, v39, v37
	s_lshl_b64 s[10:11], s[6:7], 13
	s_mov_b64 s[12:13], 0
	v_cndmask_b32_e32 v35, v35, v39, vcc
	v_lshlrev_b32_e32 v93, 2, v35
	v_and_b32_e32 v35, 63, v1
	v_lshl_or_b32 v50, v35, 3, v50
	v_lshl_add_u64 v[50:51], s[24:25], 0, v[50:51]
	v_lshl_add_u64 v[70:71], v[50:51], 0, s[8:9]
	v_lshlrev_b64 v[50:51], 13, v[66:67]
	v_lshl_or_b32 v50, v35, 4, v50
	s_waitcnt lgkmcnt(0)
	v_lshl_add_u64 v[50:51], s[0:1], 0, v[50:51]
	s_mov_b64 s[0:1], 0x1000
	s_lshl_b64 s[8:9], s[6:7], 12
	v_lshl_add_u64 v[72:73], v[50:51], 0, s[0:1]
	v_mov_b32_e32 v67, 0x358637bd
	s_mov_b32 s0, 0x800000
	s_mov_b64 s[18:19], 0x2000
	v_lshlrev_b32_e32 v68, 2, v34
	v_lshlrev_b32_e32 v74, 2, v44
	v_lshlrev_b32_e32 v76, 2, v46
	v_lshlrev_b32_e32 v78, 2, v48
	v_lshlrev_b32_e32 v80, 2, v36
	v_lshlrev_b32_e32 v82, 2, v38
	v_lshlrev_b32_e32 v84, 2, v40
	v_lshlrev_b32_e32 v86, 2, v42
	s_movk_i32 s1, 0x7fff
	.p2alignl 6, 3212836864

; __device__ __forceinline__ void post_u_rows(const Ptrs& P, int G, int bid) {
;     ...
;         for (int hf = 0; hf < 2; ++hf) {
;             const int ch = 512 * hf + 8 * lane;
;             const half8 ub = *(const half8*)(u + OFF_UB + ch), c0 = *(const half8*)(u + OFF_UC + ch), h0 = *(const half8*)(u + OFF_UH + ch);
;             half8 c1 = c0 * (h16)0, h1 = c1, c2 = c1, h2 = c1;
;             if (pos >= 1) { c1 = *(const half8*)(u - DINP + OFF_UC + ch); h1 = *(const half8*)(u - DINP + OFF_UH + ch); }
;             if (pos >= 2) { c2 = *(const half8*)(u - 2 * DINP + OFF_UC + ch); h2 = *(const half8*)(u - 2 * DINP + OFF_UH + ch); }
; #pragma unroll
;             for (int j = 0; j < 8; ++j) {
;                 const float v0 = (float)c0[j] * (float)h0[j], v1 = (float)c1[j] * (float)h1[j], v2 = (float)c2[j] * (float)h2[j];
;                 const float z = wcb[8 * hf + j] + wc0[8 * hf + j] * v2 + wc1[8 * hf + j] * v1 + wc2[8 * hf + j] * v0;
;                 const float yy = (float)ub[j] * z; y[8 * hf + j] = yy; ss += yy * yy; }
.LBB0_341:
	s_or_b64 exec, exec, s[4:5]
	v_cvt_f32_f16_e32 v146, v102
	v_cvt_f32_f16_e32 v147, v106
	v_cvt_f32_f16_e32 v164, v114
	v_cvt_f32_f16_e32 v165, v118
	v_cvt_f32_f16_e32 v166, v110
	v_cvt_f32_f16_e32 v167, v122
	v_cvt_f32_f16_sdwa v110, v110 dst_sel:DWORD dst_unused:UNUSED_PAD src0_sel:WORD_1
	v_cvt_f32_f16_sdwa v122, v122 dst_sel:DWORD dst_unused:UNUSED_PAD src0_sel:WORD_1
	v_mul_f32_e32 v146, v146, v147
	v_mul_f32_e32 v147, v164, v165
	v_mul_f32_e32 v164, v166, v167
	v_cvt_f32_f16_sdwa v102, v102 dst_sel:DWORD dst_unused:UNUSED_PAD src0_sel:WORD_1
	v_cvt_f32_f16_sdwa v106, v106 dst_sel:DWORD dst_unused:UNUSED_PAD src0_sel:WORD_1
	v_cvt_f32_f16_sdwa v114, v114 dst_sel:DWORD dst_unused:UNUSED_PAD src0_sel:WORD_1
	v_cvt_f32_f16_sdwa v118, v118 dst_sel:DWORD dst_unused:UNUSED_PAD src0_sel:WORD_1
	v_fma_f32 v164, v14, v164, v10
	v_fmac_f32_e32 v164, v26, v147
	v_fmac_f32_e32 v164, v30, v146
	v_cvt_f32_f16_e32 v146, v98
	v_mul_f32_e32 v110, v110, v122
	v_cvt_f32_f16_sdwa v98, v98 dst_sel:DWORD dst_unused:UNUSED_PAD src0_sel:WORD_1
	v_mul_f32_e32 v102, v102, v106
	v_mul_f32_e32 v106, v114, v118
	v_fma_f32 v110, v15, v110, v11
	v_fmac_f32_e32 v110, v27, v106
	v_fmac_f32_e32 v110, v31, v102
	v_mul_f32_e32 v102, v110, v98
	v_cvt_f32_f16_e32 v98, v103
	v_cvt_f32_f16_e32 v110, v107
	v_cvt_f32_f16_e32 v114, v115
	v_cvt_f32_f16_e32 v118, v119
	v_cvt_f32_f16_e32 v122, v111
	v_cvt_f32_f16_e32 v147, v123
	v_mul_f32_e32 v98, v98, v110
	v_mul_f32_e32 v110, v114, v118
	v_cvt_f32_f16_e32 v118, v99
	v_mul_f32_e32 v114, v122, v147
	v_fma_f32 v114, v16, v114, v12
	v_fmac_f32_e32 v114, v28, v110
	v_fmac_f32_e32 v114, v32, v98
	v_mul_f32_e32 v110, v114, v118
	v_cvt_f32_f16_sdwa v98, v103 dst_sel:DWORD dst_unused:UNUSED_PAD src0_sel:WORD_1
	v_cvt_f32_f16_sdwa v103, v107 dst_sel:DWORD dst_unused:UNUSED_PAD src0_sel:WORD_1
	v_cvt_f32_f16_sdwa v107, v115 dst_sel:DWORD dst_unused:UNUSED_PAD src0_sel:WORD_1
	v_cvt_f32_f16_sdwa v114, v119 dst_sel:DWORD dst_unused:UNUSED_PAD src0_sel:WORD_1
	v_cvt_f32_f16_sdwa v111, v111 dst_sel:DWORD dst_unused:UNUSED_PAD src0_sel:WORD_1
	v_cvt_f32_f16_sdwa v115, v123 dst_sel:DWORD dst_unused:UNUSED_PAD src0_sel:WORD_1
	v_mul_f32_e32 v98, v98, v103
	v_mul_f32_e32 v103, v107, v114
	v_cvt_f32_f16_sdwa v99, v99 dst_sel:DWORD dst_unused:UNUSED_PAD src0_sel:WORD_1
	v_mul_f32_e32 v107, v111, v115
	v_fma_f32 v107, v17, v107, v13
	v_fmac_f32_e32 v107, v29, v103
	v_fmac_f32_e32 v107, v33, v98
	v_mul_f32_e32 v103, v107, v99
	v_cvt_f32_f16_e32 v98, v104
	v_cvt_f32_f16_e32 v99, v108
	v_cvt_f32_f16_e32 v107, v116
	v_cvt_f32_f16_e32 v111, v120
	v_cvt_f32_f16_e32 v114, v112
	v_cvt_f32_f16_e32 v115, v124
	v_mul_f32_e32 v98, v98, v99
	v_mul_f32_e32 v99, v107, v111
	v_cvt_f32_f16_e32 v111, v100
	v_mul_f32_e32 v107, v114, v115
	v_fma_f32 v107, v22, v107, v18
	v_fmac_f32_e32 v107, v58, v99
	v_fmac_f32_e32 v107, v6, v98
	v_mul_f32_e32 v107, v107, v111
	v_cvt_f32_f16_sdwa v98, v104 dst_sel:DWORD dst_unused:UNUSED_PAD src0_sel:WORD_1
	v_cvt_f32_f16_sdwa v99, v108 dst_sel:DWORD dst_unused:UNUSED_PAD src0_sel:WORD_1
	v_cvt_f32_f16_sdwa v104, v116 dst_sel:DWORD dst_unused:UNUSED_PAD src0_sel:WORD_1
	v_cvt_f32_f16_sdwa v108, v120 dst_sel:DWORD dst_unused:UNUSED_PAD src0_sel:WORD_1
	v_cvt_f32_f16_sdwa v111, v112 dst_sel:DWORD dst_unused:UNUSED_PAD src0_sel:WORD_1
	v_cvt_f32_f16_sdwa v112, v124 dst_sel:DWORD dst_unused:UNUSED_PAD src0_sel:WORD_1
	v_mul_f32_e32 v98, v98, v99
	v_mul_f32_e32 v99, v104, v108
	v_cvt_f32_f16_sdwa v100, v100 dst_sel:DWORD dst_unused:UNUSED_PAD src0_sel:WORD_1
	v_mul_f32_e32 v104, v111, v112
	v_fma_f32 v104, v23, v104, v19
	v_fmac_f32_e32 v104, v59, v99
	v_fmac_f32_e32 v104, v7, v98
	v_mul_f32_e32 v104, v104, v100
	v_cvt_f32_f16_e32 v98, v105
	v_cvt_f32_f16_e32 v99, v109
	v_cvt_f32_f16_e32 v100, v117
	v_cvt_f32_f16_e32 v108, v121
	v_cvt_f32_f16_e32 v111, v113
	v_cvt_f32_f16_e32 v112, v125
	v_mul_f32_e32 v98, v98, v99
	v_mul_f32_e32 v99, v100, v108
	v_cvt_f32_f16_e32 v108, v101
	v_mul_f32_e32 v100, v111, v112
	v_fma_f32 v100, v24, v100, v20
	v_fmac_f32_e32 v100, v60, v99
	v_fmac_f32_e32 v100, v8, v98
	v_mul_f32_e32 v108, v100, v108
	v_cvt_f32_f16_sdwa v98, v105 dst_sel:DWORD dst_unused:UNUSED_PAD src0_sel:WORD_1
	v_cvt_f32_f16_sdwa v99, v109 dst_sel:DWORD dst_unused:UNUSED_PAD src0_sel:WORD_1
	v_cvt_f32_f16_sdwa v100, v117 dst_sel:DWORD dst_unused:UNUSED_PAD src0_sel:WORD_1
	v_cvt_f32_f16_sdwa v105, v121 dst_sel:DWORD dst_unused:UNUSED_PAD src0_sel:WORD_1
	v_cvt_f32_f16_sdwa v109, v113 dst_sel:DWORD dst_unused:UNUSED_PAD src0_sel:WORD_1
	v_cvt_f32_f16_sdwa v111, v125 dst_sel:DWORD dst_unused:UNUSED_PAD src0_sel:WORD_1
	v_mul_f32_e32 v98, v98, v99
	v_mul_f32_e32 v99, v100, v105
	v_cvt_f32_f16_sdwa v101, v101 dst_sel:DWORD dst_unused:UNUSED_PAD src0_sel:WORD_1
	v_mul_f32_e32 v100, v109, v111
	v_fma_f32 v100, v25, v100, v21
	v_fmac_f32_e32 v100, v61, v99
	v_fmac_f32_e32 v100, v9, v98
	v_mul_f32_e32 v105, v100, v101
	v_cvt_f32_f16_e32 v98, v74
	s_waitcnt vmcnt(0)
; __device__ __forceinline__ void post_u_rows(const Ptrs& P, int G, int bid) {
;     ...
;         for (int hf = 0; hf < 2; ++hf) {
;             const int ch = 512 * hf + 8 * lane;
;             const half8 ub = *(const half8*)(u + OFF_UB + ch), c0 = *(const half8*)(u + OFF_UC + ch), h0 = *(const half8*)(u + OFF_UH + ch);
;             half8 c1 = c0 * (h16)0, h1 = c1, c2 = c1, h2 = c1;
;             if (pos >= 1) { c1 = *(const half8*)(u - DINP + OFF_UC + ch); h1 = *(const half8*)(u - DINP + OFF_UH + ch); }
;             if (pos >= 2) { c2 = *(const half8*)(u - 2 * DINP + OFF_UC + ch); h2 = *(const half8*)(u - 2 * DINP + OFF_UH + ch); }
; #pragma unroll
;             for (int j = 0; j < 8; ++j) {
;                 const float v0 = (float)c0[j] * (float)h0[j], v1 = (float)c1[j] * (float)h1[j], v2 = (float)c2[j] * (float)h2[j];
;                 const float z = wcb[8 * hf + j] + wc0[8 * hf + j] * v2 + wc1[8 * hf + j] * v1 + wc2[8 * hf + j] * v0;
;                 const float yy = (float)ub[j] * z; y[8 * hf + j] = yy; ss += yy * yy; }
;         }
;         ss = wave_sum(ss); const float rstd = rsqrtf(ss * (1.f / 1024.f) + EPS);
	v_cvt_f32_f16_e32 v99, v78
	v_cvt_f32_f16_e32 v100, v86
	v_cvt_f32_f16_e32 v101, v90
	v_cvt_f32_f16_e32 v109, v82
	v_cvt_f32_f16_e32 v111, v94
	v_mul_f32_e32 v98, v98, v99
	v_mul_f32_e32 v99, v100, v101
	v_cvt_f32_f16_e32 v101, v70
	v_mul_f32_e32 v100, v109, v111
	v_fma_f32 v100, v46, v100, v42
	v_fmac_f32_e32 v100, v157, v99
	v_fmac_f32_e32 v100, v155, v98
	v_mul_f32_e32 v109, v100, v101
	v_cvt_f32_f16_sdwa v82, v82 dst_sel:DWORD dst_unused:UNUSED_PAD src0_sel:WORD_1
	v_cvt_f32_f16_sdwa v94, v94 dst_sel:DWORD dst_unused:UNUSED_PAD src0_sel:WORD_1
	v_cvt_f32_f16_sdwa v99, v86 dst_sel:DWORD dst_unused:UNUSED_PAD src0_sel:WORD_1
	v_cvt_f32_f16_sdwa v98, v74 dst_sel:DWORD dst_unused:UNUSED_PAD src0_sel:WORD_1
	v_cvt_f32_f16_sdwa v101, v90 dst_sel:DWORD dst_unused:UNUSED_PAD src0_sel:WORD_1
	v_cvt_f32_f16_sdwa v100, v78 dst_sel:DWORD dst_unused:UNUSED_PAD src0_sel:WORD_1
	v_mul_f32_e32 v74, v82, v94
	v_cvt_f32_f16_sdwa v70, v70 dst_sel:DWORD dst_unused:UNUSED_PAD src0_sel:WORD_1
	v_fma_f32 v74, v47, v74, v43
	v_pk_mul_f32 v[98:99], v[98:99], v[100:101]
	v_cvt_f32_f16_e32 v101, v91
	v_pk_mul_f32 v[98:99], v[2:3], v[98:99]
	v_cvt_f32_f16_e32 v100, v79
	v_add_f32_e32 v74, v99, v74
	v_add_f32_e32 v74, v98, v74
	v_mul_f32_e32 v90, v74, v70
	v_cvt_f32_f16_e32 v70, v83
	v_cvt_f32_f16_e32 v74, v95
	v_cvt_f32_f16_e32 v99, v87
	v_cvt_f32_f16_e32 v98, v75
	v_cvt_f32_f16_sdwa v78, v95 dst_sel:DWORD dst_unused:UNUSED_PAD src0_sel:WORD_1
	v_mul_f32_e32 v70, v70, v74
	v_cvt_f32_f16_e32 v74, v71
	v_pk_mul_f32 v[98:99], v[98:99], v[100:101]
	v_fma_f32 v70, v48, v70, v44
	v_pk_mul_f32 v[98:99], v[136:137], v[98:99]
	v_cvt_f32_f16_sdwa v82, v75 dst_sel:DWORD dst_unused:UNUSED_PAD src0_sel:WORD_1
	v_add_f32_e32 v70, v99, v70
	v_add_f32_e32 v70, v98, v70
	v_mul_f32_e32 v94, v70, v74
	v_cvt_f32_f16_sdwa v70, v83 dst_sel:DWORD dst_unused:UNUSED_PAD src0_sel:WORD_1
	v_cvt_f32_f16_sdwa v83, v87 dst_sel:DWORD dst_unused:UNUSED_PAD src0_sel:WORD_1
	v_cvt_f32_f16_sdwa v75, v91 dst_sel:DWORD dst_unused:UNUSED_PAD src0_sel:WORD_1
	v_cvt_f32_f16_sdwa v74, v79 dst_sel:DWORD dst_unused:UNUSED_PAD src0_sel:WORD_1
	v_mul_f32_e32 v70, v70, v78
	v_fma_f32 v70, v49, v70, v45
	v_cvt_f32_f16_e32 v79, v92
	v_pk_mul_f32 v[74:75], v[82:83], v[74:75]
	v_cvt_f32_f16_sdwa v82, v71 dst_sel:DWORD dst_unused:UNUSED_PAD src0_sel:WORD_1
	v_pk_mul_f32 v[74:75], v[4:5], v[74:75]
	v_cvt_f32_f16_e32 v71, v88
	v_add_f32_e32 v75, v75, v70
	v_cvt_f32_f16_e32 v70, v76
	v_cvt_f32_f16_e32 v78, v80
	v_add_f32_e32 v74, v74, v75
	v_mul_f32_e32 v91, v74, v82
	v_cvt_f32_f16_sdwa v75, v88 dst_sel:DWORD dst_unused:UNUSED_PAD src0_sel:WORD_1
	v_pk_mul_f32 v[70:71], v[70:71], v[78:79]
	v_cvt_f32_f16_sdwa v74, v76 dst_sel:DWORD dst_unused:UNUSED_PAD src0_sel:WORD_1
	v_cvt_f32_f16_sdwa v79, v92 dst_sel:DWORD dst_unused:UNUSED_PAD src0_sel:WORD_1
	v_cvt_f32_f16_sdwa v78, v80 dst_sel:DWORD dst_unused:UNUSED_PAD src0_sel:WORD_1
	v_mul_f32_e32 v146, v164, v146
	v_mul_f32_e32 v106, v102, v102
	v_cvt_f32_f16_sdwa v83, v84 dst_sel:DWORD dst_unused:UNUSED_PAD src0_sel:WORD_1
	v_cvt_f32_f16_e32 v82, v84
	v_cvt_f32_f16_sdwa v87, v96 dst_sel:DWORD dst_unused:UNUSED_PAD src0_sel:WORD_1
	v_cvt_f32_f16_e32 v86, v96
	v_fmac_f32_e32 v106, v146, v146
	v_fmac_f32_e32 v106, v110, v110
	v_fmac_f32_e32 v106, v103, v103
	v_pk_mul_f32 v[74:75], v[74:75], v[78:79]
	v_fmac_f32_e32 v106, v107, v107
	v_pk_mul_f32 v[70:71], v[134:135], v[70:71]
	v_pk_mul_f32 v[74:75], v[126:127], v[74:75]
	v_pk_mul_f32 v[78:79], v[82:83], v[86:87]
	v_cvt_f32_f16_sdwa v87, v72 dst_sel:DWORD dst_unused:UNUSED_PAD src0_sel:WORD_1
	v_cvt_f32_f16_e32 v86, v72
	v_fmac_f32_e32 v106, v104, v104
	v_pk_fma_f32 v[78:79], v[54:55], v[78:79], v[50:51]
	v_mov_b32_e32 v82, v71
	v_mov_b32_e32 v83, v75
	v_fmac_f32_e32 v106, v108, v108
	v_pk_add_f32 v[78:79], v[82:83], v[78:79]
	v_mov_b32_e32 v71, v74
	v_fmac_f32_e32 v106, v105, v105
	v_pk_add_f32 v[70:71], v[70:71], v[78:79]
	v_fmac_f32_e32 v106, v109, v109
	v_pk_mul_f32 v[74:75], v[70:71], v[86:87]
	v_cvt_f32_f16_e32 v71, v89
	v_cvt_f32_f16_e32 v70, v77
	v_cvt_f32_f16_e32 v79, v93
	v_cvt_f32_f16_e32 v78, v81
	v_fmac_f32_e32 v106, v90, v90
	v_fmac_f32_e32 v106, v94, v94
	v_fmac_f32_e32 v106, v91, v91
	v_pk_mul_f32 v[82:83], v[74:75], v[74:75]
	v_pk_mul_f32 v[70:71], v[70:71], v[78:79]
	v_add_f32_e32 v72, v82, v106
	v_cvt_f32_f16_sdwa v79, v89 dst_sel:DWORD dst_unused:UNUSED_PAD src0_sel:WORD_1
	v_cvt_f32_f16_sdwa v78, v77 dst_sel:DWORD dst_unused:UNUSED_PAD src0_sel:WORD_1
	v_cvt_f32_f16_sdwa v77, v93 dst_sel:DWORD dst_unused:UNUSED_PAD src0_sel:WORD_1
	v_cvt_f32_f16_sdwa v76, v81 dst_sel:DWORD dst_unused:UNUSED_PAD src0_sel:WORD_1
	v_add_f32_e32 v84, v83, v72
	v_cvt_f32_f16_sdwa v81, v85 dst_sel:DWORD dst_unused:UNUSED_PAD src0_sel:WORD_1
	v_cvt_f32_f16_e32 v80, v85
	v_cvt_f32_f16_sdwa v83, v97 dst_sel:DWORD dst_unused:UNUSED_PAD src0_sel:WORD_1
	v_cvt_f32_f16_e32 v82, v97
	v_pk_mul_f32 v[76:77], v[78:79], v[76:77]
	v_pk_mul_f32 v[70:71], v[132:133], v[70:71]
	v_pk_mul_f32 v[76:77], v[128:129], v[76:77]
	v_pk_mul_f32 v[78:79], v[80:81], v[82:83]
	v_cvt_f32_f16_sdwa v83, v73 dst_sel:DWORD dst_unused:UNUSED_PAD src0_sel:WORD_1
	v_cvt_f32_f16_e32 v82, v73
	v_pk_fma_f32 v[78:79], v[56:57], v[78:79], v[52:53]
	v_mov_b32_e32 v80, v71
	v_mov_b32_e32 v81, v77
	v_pk_add_f32 v[72:73], v[80:81], v[78:79]
	v_mov_b32_e32 v71, v76
	v_pk_add_f32 v[70:71], v[70:71], v[72:73]
	v_add_u32_e32 v130, s10, v130
	v_pk_mul_f32 v[76:77], v[70:71], v[82:83]
	v_lshl_add_u64 v[140:141], v[140:141], 0, s[20:21]
	v_pk_mul_f32 v[70:71], v[76:77], v[76:77]
	v_lshl_add_u64 v[142:143], v[142:143], 0, s[20:21]
	v_add_f32_e32 v70, v70, v84
	v_add_f32_e32 v70, v71, v70
	ds_bpermute_b32 v71, v158, v70
	v_lshl_add_u64 v[144:145], v[144:145], 0, s[20:21]
	s_waitcnt lgkmcnt(0)
; __device__ __forceinline__ unsigned pk_bf2(float lo, float hi) { unsigned r; asm("v_cvt_pk_bf16_f32 %0, %1, %2" : "=v"(r) : "v"(lo), "v"(hi)); return r; }
; __device__ __forceinline__ void post_u_rows(const Ptrs& P, int G, int bid) {
;     ...
;         ss = wave_sum(ss); const float rstd = rsqrtf(ss * (1.f / 1024.f) + EPS);
; #pragma unroll
;         for (int hf = 0; hf < 2; ++hf) { const int ch = 512 * hf + 8 * lane; float f[8];
; #pragma unroll
;             for (int j = 0; j < 8; ++j) f[j] = y[8 * hf + j] * rstd * wg[8 * hf + j];
;             u32x4 o; o.x = pg8::pk_bf2(f[0], f[1]); o.y = pg8::pk_bf2(f[2], f[3]); o.z = pg8::pk_bf2(f[4], f[5]); o.w = pg8::pk_bf2(f[6], f[7]);
;             *(u32x4*)(MIX + (size_t)r * DM + ch) = o; }
	v_add_f32_e32 v70, v70, v71
	ds_bpermute_b32 v71, v159, v70
	s_waitcnt lgkmcnt(0)
	v_add_f32_e32 v70, v70, v71
	ds_bpermute_b32 v71, v160, v70
	s_waitcnt lgkmcnt(0)
	v_add_f32_e32 v70, v70, v71
	ds_bpermute_b32 v71, v161, v70
	s_waitcnt lgkmcnt(0)
	v_add_f32_e32 v70, v70, v71
	ds_bpermute_b32 v71, v162, v70
	s_waitcnt lgkmcnt(0)
	v_add_f32_e32 v70, v70, v71
	ds_bpermute_b32 v71, v163, v70
	s_waitcnt lgkmcnt(0)
	v_add_f32_e32 v70, v70, v71
	v_fmamk_f32 v70, v70, 0x3a800000, v131
	v_mul_f32_e32 v71, 0x4b800000, v70
	v_cmp_gt_f32_e32 vcc, s1, v70
	s_nop 1
	v_cndmask_b32_e32 v70, v70, v71, vcc
	v_rsq_f32_e32 v70, v70
	s_nop 0
	v_mul_f32_e32 v71, 0x45800000, v70
	v_cndmask_b32_e32 v80, v70, v71, vcc
	v_mul_f32_e32 v70, v146, v80
	v_mul_f32_e32 v71, v102, v80
	v_mul_f32_e32 v72, v110, v80
	v_mul_f32_e32 v78, v107, v80
	v_mul_f32_e32 v79, v104, v80
	v_mul_f32_e32 v70, v34, v70
	v_mul_f32_e32 v71, v35, v71
	v_mul_f32_e32 v72, v36, v72
	v_mul_f32_e32 v73, v103, v80
	v_mul_f32_e32 v78, v38, v78
	v_mul_f32_e32 v79, v39, v79
	v_mul_f32_e32 v73, v37, v73
	v_cvt_pk_bf16_f32 v70, v70, v71
	v_cvt_pk_bf16_f32 v71, v72, v73
	v_cvt_pk_bf16_f32 v72, v78, v79
	v_lshl_add_u64 v[78:79], s[24:25], 0, v[138:139]
	v_mul_f32_e32 v81, v108, v80
	v_mul_f32_e32 v82, v105, v80
	v_add_co_u32_e32 v78, vcc, s3, v78
	v_mul_f32_e32 v81, v40, v81
	v_mul_f32_e32 v82, v41, v82
	v_cvt_pk_bf16_f32 v73, v81, v82
	v_addc_co_u32_e32 v79, vcc, 0, v79, vcc
	global_store_dwordx4 v[78:79], v[70:73], off
	v_cmp_lt_i32_e32 vcc, s11, v130
	v_mul_f32_e32 v74, v74, v80
	v_mul_f32_e32 v70, v109, v80
	v_mul_f32_e32 v71, v90, v80
	v_mul_f32_e32 v72, v94, v80
	v_mul_f32_e32 v73, v91, v80
	v_mul_f32_e32 v70, v62, v70
	v_mul_f32_e32 v71, v63, v71
	v_mul_f32_e32 v72, v64, v72
	v_mul_f32_e32 v73, v65, v73
	v_mul_f32_e32 v75, v75, v80
	v_mul_f32_e32 v76, v76, v80
	v_mul_f32_e32 v77, v77, v80
	v_lshl_add_u64 v[138:139], v[138:139], 0, s[18:19]
	s_or_b64 s[22:23], vcc, s[22:23]
	v_mul_f32_e32 v74, v66, v74
	v_mul_f32_e32 v75, v67, v75
	v_mul_f32_e32 v76, v68, v76
	v_mul_f32_e32 v77, v69, v77
	v_cvt_pk_bf16_f32 v70, v70, v71
	v_cvt_pk_bf16_f32 v71, v72, v73
	v_cvt_pk_bf16_f32 v72, v74, v75
	v_cvt_pk_bf16_f32 v73, v76, v77
	global_store_dwordx4 v[78:79], v[70:73], off offset:1024
	s_andn2_b64 exec, exec, s[22:23]
	s_cbranch_execz .LBB0_352
	.p2alignl 6, 3212836864

; #define CP_LOADB(buf_, pos_) do { _Pragma("unroll") for (int ks = 0; ks < 4; ++ks) _Pragma("unroll") for (int nt = 0; nt < 2; ++nt) fb[buf_][ks][nt] = *(const half8*)(brow[nt] + (pos_) * 128 + 32 * ks); } while (0)
; __device__ __forceinline__ void compress_phase(const Ptrs& P, LAS unsigned char* lds, int G, int bid) {
;     ...
;         for (int pos = 0; pos < 33; pos += 3) {
;             if (pos + 2 < 32) CP_LOADB(2, pos + 2);
;             CP_MMA(0, pos);
;             if (pos + 3 < 32) CP_LOADB(0, pos + 3);
;             if (pos + 1 < 32) CP_MMA(1, pos + 1);
;             if (pos + 4 < 32) CP_LOADB(1, pos + 4);
;             if (pos + 2 < 32) CP_MMA(2, pos + 2);
;         }
.LBB0_429:
	s_add_i32 s11, s11, 3
	v_lshl_add_u64 v[132:133], v[132:133], 0, s[18:19]
	v_add_u32_e32 v131, 0x300, v131
	s_and_b64 vcc, exec, s[20:21]
	s_cbranch_vccnz .LBB0_419
	.p2alignl 6, 3212836864

; template <bool BF> __device__ __forceinline__ unsigned pk2(float lo, float hi) { return BF ? pk_bf2(lo, hi) : pk_h2(lo, hi); }
; template <bool BF, bool IN_F16> __device__ __forceinline__ void norm_mod_rows(const void* __restrict__ Xv, const float* __restrict__ gw, const float* __restrict__ mod, int sh_off, int sc_off,
;                                               h16* __restrict__ H, int G, int bid) {
;     const int lane = threadIdx.x & 63, wave = threadIdx.x >> 6;
;     for (int r = bid * 8 + wave; r < NT; r += G * 8) {
;         const int b = r >> 13; f32x4 v[8]; float ss = 0.f;
;         if (IN_F16) { const h16* xr = (const h16*)Xv + (size_t)r * DM;
; #pragma unroll
;             for (int i = 0; i < 8; ++i) { const half4 hv = *(const half4*)(xr + 4 * (lane + 64 * i)); v[i] = (f32x4){(float)hv[0], (float)hv[1], (float)hv[2], (float)hv[3]}; } }
;         else { const float* xr = (const float*)Xv + (size_t)r * DM;
; #pragma unroll
;             for (int i = 0; i < 8; ++i) v[i] = *(const f32x4*)(xr + 4 * (lane + 64 * i)); }
; #pragma unroll
;         for (int i = 0; i < 8; ++i) ss += v[i][0] * v[i][0] + v[i][1] * v[i][1] + v[i][2] * v[i][2] + v[i][3] * v[i][3];
;         ss = wave_sum(ss); const float rstd = rsqrtf(ss * (1.f / DM) + EPS);
;         const float* mb = mod + (size_t)b * 12288;
; #pragma unroll
;         for (int i = 0; i < 8; ++i) { const int c = 4 * (lane + 64 * i);
;             const f32x4 g = *(const f32x4*)(gw + c), sh = *(const f32x4*)(mb + sh_off + c), sc = *(const f32x4*)(mb + sc_off + c);
;             const f32x4 o = (v[i] * rstd) * g * (1.f + sc) + sh;
;             u32x2 w; w.x = pg8::pk2<BF>(o[0], o[1]); w.y = pg8::pk2<BF>(o[2], o[3]);
;             *(u32x2*)(H + (size_t)r * DM + c) = w; }
.LBB0_782:
.LBB0_783:
	s_cmp_lt_i32 s26, 9
	s_cselect_b64 s[0:1], -1, 0
	s_cmp_gt_i32 s27, 8
	s_cselect_b64 s[4:5], -1, 0
	s_and_b64 s[0:1], s[0:1], s[4:5]
	s_andn2_b64 vcc, exec, s[0:1]
	s_cbranch_vccnz .LBB0_851
	v_lshrrev_b32_e32 v2, 6, v1
	v_lshl_add_u32 v26, s2, 3, v2
	s_mov_b32 s0, 0x8000
	v_cmp_gt_i32_e32 vcc, s0, v26
	s_and_saveexec_b64 s[4:5], vcc
	s_cbranch_execz .LBB0_787
	s_load_dwordx2 s[8:9], s[96:97], 0x88
	v_lshlrev_b32_e32 v2, 2, v1
	v_and_b32_e32 v6, 0xfc, v2
	v_mbcnt_lo_u32_b32 v2, -1, 0
	v_lshlrev_b32_e32 v28, 2, v6
	v_mbcnt_hi_u32_b32 v7, -1, v2
	s_waitcnt lgkmcnt(0)
	global_load_dwordx4 v[2:5], v28, s[8:9]
	v_and_b32_e32 v8, 64, v7
	v_add_u32_e32 v8, 64, v8
	v_xor_b32_e32 v9, 1, v7
	v_cmp_lt_i32_e32 vcc, v9, v8
	v_mov_b32_e32 v29, 0
	v_or_b32_e32 v14, 0x400, v6
	v_cndmask_b32_e32 v9, v7, v9, vcc
	v_lshlrev_b32_e32 v76, 2, v9
	v_xor_b32_e32 v9, 2, v7
	v_cmp_lt_i32_e32 vcc, v9, v8
	v_lshl_add_u64 v[30:31], s[8:9], 0, v[28:29]
	v_or_b32_e32 v16, 0x500, v6
	v_cndmask_b32_e32 v9, v7, v9, vcc
	v_lshlrev_b32_e32 v77, 2, v9
	v_xor_b32_e32 v9, 4, v7
	v_cmp_lt_i32_e32 vcc, v9, v8
	v_lshlrev_b32_e32 v28, 2, v14
	v_ashrrev_i32_e32 v27, 31, v26
	v_cndmask_b32_e32 v9, v7, v9, vcc
	v_lshlrev_b32_e32 v78, 2, v9
	v_xor_b32_e32 v9, 8, v7
	v_cmp_lt_i32_e32 vcc, v9, v8
	v_or_b32_e32 v18, 0x600, v6
	v_lshl_add_u64 v[32:33], s[8:9], 0, v[28:29]
	v_cndmask_b32_e32 v9, v7, v9, vcc
	v_lshlrev_b32_e32 v79, 2, v9
	v_xor_b32_e32 v9, 16, v7
	v_cmp_lt_i32_e32 vcc, v9, v8
	v_lshlrev_b32_e32 v28, 2, v16
	v_lshlrev_b64 v[22:23], 12, v[26:27]
	v_cndmask_b32_e32 v9, v7, v9, vcc
	v_lshlrev_b32_e32 v80, 2, v9
	v_xor_b32_e32 v9, 32, v7
	v_cmp_lt_i32_e32 vcc, v9, v8
	s_lshl_b32 s6, s95, 3
	v_or_b32_e32 v20, 0x700, v6
	v_cndmask_b32_e32 v7, v7, v9, vcc
	v_lshlrev_b32_e32 v81, 2, v7
	v_and_b32_e32 v7, 63, v1
	v_lshl_add_u64 v[34:35], s[8:9], 0, v[28:29]
	v_lshlrev_b32_e32 v28, 2, v18
	v_lshl_or_b32 v22, v7, 3, v22
	v_or_b32_e32 v8, 0x100, v6
	v_or_b32_e32 v10, 0x200, v6
	v_or_b32_e32 v12, 0x300, v6
	v_lshl_add_u64 v[36:37], s[8:9], 0, v[28:29]
	v_lshlrev_b32_e32 v28, 2, v20
	v_lshl_add_u64 v[22:23], s[24:25], 0, v[22:23]
	s_mov_b64 s[0:1], 0x2e564000
	s_ashr_i32 s7, s6, 31
	v_lshl_add_u64 v[38:39], s[8:9], 0, v[28:29]
	v_lshl_add_u64 v[40:41], v[22:23], 0, s[0:1]
	s_lshl_b64 s[8:9], s[6:7], 12
	s_mov_b64 s[10:11], 0
	v_mov_b32_e32 v27, 0x358637bd
	s_mov_b32 s0, 0x800000
	s_mov_b64 s[12:13], 0x6000
	s_mov_b64 s[18:19], 0x8000
	v_lshlrev_b32_e32 v28, 2, v6
	s_brev_b32 s1, 27
	v_lshlrev_b32_e32 v42, 2, v8
	s_mov_b32 s3, 0xd8001000
	v_lshlrev_b32_e32 v44, 2, v10
	v_lshlrev_b32_e32 v46, 2, v12
	v_lshlrev_b32_e32 v48, 2, v14
	v_lshlrev_b32_e32 v50, 2, v16
	v_lshlrev_b32_e32 v52, 2, v18
	v_lshlrev_b32_e32 v54, 2, v20
	s_movk_i32 s7, 0x7fff
	v_mov_b32_e32 v43, v29
	v_mov_b32_e32 v45, v29
	v_mov_b32_e32 v47, v29
	v_mov_b32_e32 v49, v29
	v_mov_b32_e32 v51, v29
	v_mov_b32_e32 v53, v29
	v_mov_b32_e32 v55, v29
	.p2alignl 6, 3212836864

; __device__ __forceinline__ void final_norm_rows(const h16* __restrict__ X, float* __restrict__ O, const float* __restrict__ gw, int G, int bid) {
;     const int lane = threadIdx.x & 63, wave = threadIdx.x >> 6;
;     for (int r = bid * 8 + wave; r < NT; r += G * 8) {
;         const h16* xr = X + (size_t)r * DM; f32x4 v[8]; float ss = 0.f;
; #pragma unroll
;         for (int i = 0; i < 8; ++i) { const half4 hv = *(const half4*)(xr + 4 * (lane + 64 * i)); v[i] = (f32x4){(float)hv[0], (float)hv[1], (float)hv[2], (float)hv[3]};
;             ss += v[i][0] * v[i][0] + v[i][1] * v[i][1] + v[i][2] * v[i][2] + v[i][3] * v[i][3]; }
;         ss = wave_sum(ss); const float rstd = rsqrtf(ss * (1.f / DM) + EPS);
; #pragma unroll
;         for (int i = 0; i < 8; ++i) { const int c = 4 * (lane + 64 * i); const f32x4 g = *(const f32x4*)(gw + c); *(f32x4*)(O + (size_t)r * DM + c) = (v[i] * rstd) * g; }
.LBB0_1029:
	s_cmp_lt_i32 s26, 12
	s_cselect_b64 s[0:1], -1, 0
	s_cmp_gt_i32 s27, 11
	s_cselect_b64 s[4:5], -1, 0
	s_and_b64 s[0:1], s[0:1], s[4:5]
	s_andn2_b64 vcc, exec, s[0:1]
	s_cbranch_vccnz .LBB0_1097
	v_lshrrev_b32_e32 v2, 6, v1
	v_lshl_add_u32 v34, s2, 3, v2
	s_mov_b32 s0, 0x8000
	v_cmp_gt_i32_e32 vcc, s0, v34
	s_and_saveexec_b64 s[2:3], vcc
	s_cbranch_execz .LBB0_1033
	s_load_dwordx4 s[4:7], s[96:97], 0xa0
	v_lshlrev_b32_e32 v2, 4, v1
	v_and_b32_e32 v26, 0x3f0, v2
	v_or_b32_e32 v27, 0x1000, v26
	v_or_b32_e32 v28, 0x1400, v26
	s_waitcnt lgkmcnt(0)
	global_load_dwordx4 v[2:5], v26, s[4:5]
	global_load_dwordx4 v[6:9], v26, s[4:5] offset:1024
	global_load_dwordx4 v[10:13], v26, s[4:5] offset:2048
	global_load_dwordx4 v[14:17], v26, s[4:5] offset:3072
	v_or_b32_e32 v35, 0x1800, v26
	global_load_dwordx4 v[18:21], v27, s[4:5]
	global_load_dwordx4 v[22:25], v28, s[4:5]
	v_or_b32_e32 v36, 0x1c00, v26
	global_load_dwordx4 v[26:29], v35, s[4:5]
	global_load_dwordx4 v[30:33], v36, s[4:5]
	v_mbcnt_lo_u32_b32 v35, -1, 0
	v_mbcnt_hi_u32_b32 v35, -1, v35
	v_and_b32_e32 v36, 64, v35
	v_add_u32_e32 v36, 64, v36
	v_xor_b32_e32 v37, 1, v35
	v_cmp_lt_i32_e32 vcc, v37, v36
	v_and_b32_e32 v46, 63, v1
	s_lshl_b32 s0, s95, 3
	v_cndmask_b32_e32 v37, v35, v37, vcc
	v_lshlrev_b32_e32 v40, 2, v37
	v_xor_b32_e32 v37, 2, v35
	v_cmp_lt_i32_e32 vcc, v37, v36
	s_mov_b64 s[4:5], 0x2e564000
	s_ashr_i32 s1, s0, 31
	v_cndmask_b32_e32 v37, v35, v37, vcc
	v_lshlrev_b32_e32 v41, 2, v37
	v_xor_b32_e32 v37, 4, v35
	v_cmp_lt_i32_e32 vcc, v37, v36
	s_mov_b64 s[8:9], 0
	s_movk_i32 s10, 0x7fff
	v_cndmask_b32_e32 v37, v35, v37, vcc
	v_lshlrev_b32_e32 v42, 2, v37
	v_xor_b32_e32 v37, 8, v35
	v_cmp_lt_i32_e32 vcc, v37, v36
	s_nop 1
	v_cndmask_b32_e32 v37, v35, v37, vcc
	v_lshlrev_b32_e32 v43, 2, v37
	v_xor_b32_e32 v37, 16, v35
	v_cmp_lt_i32_e32 vcc, v37, v36
	s_nop 1
	v_cndmask_b32_e32 v37, v35, v37, vcc
	v_lshlrev_b32_e32 v44, 2, v37
	v_xor_b32_e32 v37, 32, v35
	v_cmp_lt_i32_e32 vcc, v37, v36
	s_nop 1
	v_cndmask_b32_e32 v35, v35, v37, vcc
	v_lshlrev_b32_e32 v45, 2, v35
	v_ashrrev_i32_e32 v35, 31, v34
	v_lshlrev_b64 v[36:37], 12, v[34:35]
	v_lshlrev_b64 v[38:39], 13, v[34:35]
	v_lshl_or_b32 v36, v46, 3, v36
	v_lshl_or_b32 v38, v46, 4, v38
	v_lshl_add_u64 v[36:37], s[24:25], 0, v[36:37]
	v_lshl_add_u64 v[38:39], s[6:7], 0, v[38:39]
	s_mov_b64 s[6:7], 0x1000
	v_lshl_add_u64 v[36:37], v[36:37], 0, s[4:5]
	s_lshl_b64 s[4:5], s[0:1], 12
	v_lshl_add_u64 v[38:39], v[38:39], 0, s[6:7]
	s_lshl_b64 s[6:7], s[0:1], 13
	v_mov_b32_e32 v35, 0x358637bd
	s_mov_b32 s1, 0x800000
	.p2alignl 6, 3212836864
